# grid barrier: non-leader workgroups sleep 6 instead of 1 between polls of the generation word (less traffic on the word the releasing atomic targets)
# speedup vs baseline: 1.0046x; 1.0046x over previous
; DI unsigned xb_ld(unsigned* p)              { return __hip_atomic_load(p, __ATOMIC_RELAXED, __HIP_MEMORY_SCOPE_AGENT); }
; DI unsigned xb_add(unsigned* p, unsigned v) { return __hip_atomic_fetch_add(p, v, __ATOMIC_RELAXED, __HIP_MEMORY_SCOPE_AGENT); }
; #define XB_SPIN(cond, bar) do { unsigned _sp = 0; while (cond) { __builtin_amdgcn_s_sleep(1); \
;     if ((++_sp & 255u) == 0u) { if (xb_ld(&(bar)[XB_TMO])) break; if (_sp > XB_SPIN_CAP) { atomicAdd(&(bar)[XB_TMO], 1u); break; } } } } while (0)
; DI void xcd_barrier(const XcdBarrier& b) {
;     ...
;             else XB_SPIN(xb_ld(&bar[XB_TOPGEN]) == tg, bar);
;             __builtin_amdgcn_fence(__ATOMIC_ACQUIRE, "agent");
;             xb_add(&bar[XB_XGEN(b.x)], 1u);
;             asm volatile("s_waitcnt vmcnt(0)" ::: "memory");
;         } else {
;             XB_SPIN(xb_ld(&bar[XB_XGEN(b.x)]) == gen, bar);
;             __builtin_amdgcn_fence(__ATOMIC_ACQUIRE, "agent");
;             asm volatile("s_waitcnt vmcnt(0)" ::: "memory");
;         }
.LBB0_375:
	s_and_b32 s42, s46, 0xff
	s_mov_b64 s[40:41], -1
	s_cmp_lg_u32 s42, 0
	s_mov_b64 s[44:45], -1
	s_sleep 6
	s_cbranch_scc0 .LBB0_378
	s_and_b64 vcc, exec, s[44:45]
	s_cbranch_vccz .LBB0_374
